# nt hint on the FFN gate|up epilogue stores of hid (bf16 hidden activations); cache-policy experiment on top of v022
# baseline (speedup 1.0000x reference)
; __device__ __forceinline__ float silu_mul(float g, float u) { return g * u * __builtin_amdgcn_rcpf(1.0f + __builtin_amdgcn_exp2f(-g * LOG2E)); }
;     __device__ __forceinline__ void operator()(const i32x4 (&acc)[2][2][4][2], const pg8::Unit& u, int wr, int wc, int fr, int fq) const {
;         const int row0 = u.pm * 256 + wr * 64 + fr, col0 = u.pn * 128 + wc * 32 + 8 * fq, ch0 = u.pn * 256 + wc * 32 + 8 * fq;
;         const f32x4 sg0 = *(const f32x4*)(sb + ch0), sg1 = *(const f32x4*)(sb + ch0 + 4), su0 = *(const f32x4*)(sb + ch0 + 128), su1 = *(const f32x4*)(sb + ch0 + 132);
;         float rr[2][4];
; #pragma unroll
;         for (int ai = 0; ai < 2; ++ai)
; #pragma unroll
;             for (int m = 0; m < 4; ++m) rr[ai][m] = ra[row0 + ai * 128 + m * 16];
; #pragma unroll
;         for (int ai = 0; ai < 2; ++ai)
; #pragma unroll
;             for (int m = 0; m < 4; ++m) {
;                 const int row = row0 + ai * 128 + m * 16; const float r = rr[ai][m];
;                 f32x4 g0, g1, u0, u1;
; #pragma unroll
;                 for (int e = 0; e < 4; ++e) { g0[e] = (float)acc[ai][0][m][0][e] * r * sg0[e]; g1[e] = (float)acc[ai][0][m][1][e] * r * sg1[e]; u0[e] = (float)acc[ai][1][m][0][e] * r * su0[e]; u1[e] = (float)acc[ai][1][m][1][e] * r * su1[e]; }
;                 float h0 = silu_mul(g0[0], u0[0]), h1 = silu_mul(g0[1], u0[1]), h2 = silu_mul(g0[2], u0[2]), h3 = silu_mul(g0[3], u0[3]);
;                 float h4 = silu_mul(g1[0], u1[0]), h5 = silu_mul(g1[1], u1[1]), h6 = silu_mul(g1[2], u1[2]), h7 = silu_mul(g1[3], u1[3]);
.LBB0_1172:
	s_lshl_b32 s11, s18, 8
	s_add_i32 s13, s11, s41
	v_lshl_or_b32 v90, s19, 8, v168
	v_or_b32_e32 v180, s13, v161
	v_ashrrev_i32_e32 v91, 31, v90
	v_ashrrev_i32_e32 v181, 31, v180
	v_lshl_add_u64 v[90:91], v[90:91], 2, s[6:7]
	v_lshl_add_u64 v[182:183], v[180:181], 2, s[4:5]
	global_load_dwordx4 v[172:175], v[90:91], off
	global_load_dwordx4 v[98:101], v[90:91], off offset:512
	global_load_dwordx4 v[176:179], v[90:91], off offset:16
	s_nop 0
	global_load_dwordx4 v[90:93], v[90:91], off offset:528
	v_or_b32_e32 v166, 16, v180
	global_load_dword v146, v[182:183], off
	v_or_b32_e32 v162, 32, v180
	v_or_b32_e32 v158, 48, v180
	v_ashrrev_i32_e32 v167, 31, v166
	v_ashrrev_i32_e32 v163, 31, v162
	v_ashrrev_i32_e32 v159, 31, v158
	v_cvt_f32_i32_e32 v185, v126
	v_cvt_f32_i32_e32 v184, v134
	v_cvt_f32_i32_e32 v187, v122
	v_cvt_f32_i32_e32 v189, v127
	v_cvt_f32_i32_e32 v191, v123
	v_cvt_f32_i32_e32 v193, v128
	v_cvt_f32_i32_e32 v192, v136
	v_cvt_f32_i32_e32 v195, v124
	v_cvt_f32_i32_e32 v194, v132
	v_cvt_f32_i32_e32 v197, v129
	v_cvt_f32_i32_e32 v199, v125
	v_cvt_f32_i32_e32 v198, v133
	v_add_u32_e32 v133, 0x80, v180
	v_lshlrev_b32_e32 v123, 7, v180
	v_lshl_add_u64 v[124:125], v[166:167], 2, s[4:5]
	v_lshl_add_u64 v[126:127], v[162:163], 2, s[4:5]
	v_lshl_add_u64 v[128:129], v[158:159], 2, s[4:5]
	global_load_dword v136, v[182:183], off offset:512
	global_load_dword v134, v[182:183], off offset:576
	global_load_dword v132, v[182:183], off offset:640
	global_load_dword v180, v[124:125], off
	global_load_dword v164, v[126:127], off
	global_load_dword v160, v[128:129], off
	global_load_dword v122, v[182:183], off offset:704
	v_cvt_f32_i32_e32 v188, v135
	v_cvt_f32_i32_e32 v186, v130
	v_cvt_f32_i32_e32 v190, v131
	v_cvt_f32_i32_e32 v196, v137
	v_cvt_f32_i32_e32 v111, v111
	s_lshl_b32 s11, s19, 7
	s_or_b32 s11, s11, s42
	s_ashr_i32 s13, s13, 8
	v_cvt_f32_i32_e32 v113, v113
	s_ashr_i32 s11, s11, 6
	s_mulk_i32 s13, 0xac
	s_add_i32 s18, s13, s11
	s_ashr_i32 s19, s18, 31
	s_lshl_b64 s[18:19], s[18:19], 15
	s_add_u32 s18, s84, s18
	s_addc_u32 s19, s85, s19
	v_cvt_f32_i32_e32 v107, v107
	v_cvt_f32_i32_e32 v109, v109
	v_cvt_f32_i32_e32 v87, v87
	v_cvt_f32_i32_e32 v89, v89
	v_cvt_f32_i32_e32 v83, v83
	v_cvt_f32_i32_e32 v85, v85
	v_cvt_f32_i32_e32 v71, v71
	v_cvt_f32_i32_e32 v73, v73
	v_cvt_f32_i32_e32 v67, v67
	v_cvt_f32_i32_e32 v69, v69
	v_cvt_f32_i32_e32 v55, v55
	v_cvt_f32_i32_e32 v57, v57
	v_cvt_f32_i32_e32 v51, v51
	v_cvt_f32_i32_e32 v53, v53
	v_cvt_f32_i32_e32 v39, v39
	v_cvt_f32_i32_e32 v41, v41
	v_cvt_f32_i32_e32 v35, v35
	v_cvt_f32_i32_e32 v37, v37
	v_cvt_f32_i32_e32 v23, v23
	v_cvt_f32_i32_e32 v25, v25
	v_cvt_f32_i32_e32 v19, v19
	v_cvt_f32_i32_e32 v21, v21
	v_cvt_f32_i32_e32 v7, v7
	v_cvt_f32_i32_e32 v9, v9
	v_cvt_f32_i32_e32 v3, v3
	v_cvt_f32_i32_e32 v5, v5
	s_andn2_b64 vcc, exec, s[2:3]
	s_mov_b64 s[2:3], -1
	s_waitcnt vmcnt(0)
	v_mov_b32_e32 v130, v172
	v_mov_b32_e32 v131, v98
	v_mov_b32_e32 v128, v176
	v_mov_b32_e32 v129, v90
	v_mov_b32_e32 v98, v173
	v_mov_b32_e32 v90, v177
	v_pk_mul_f32 v[172:173], v[146:147], v[184:185] op_sel_hi:[0,1]
	v_pk_mul_f32 v[176:177], v[146:147], v[188:189] op_sel_hi:[0,1]
	v_pk_mul_f32 v[172:173], v[130:131], v[172:173]
	v_pk_mul_f32 v[176:177], v[98:99], v[176:177]
	v_mov_b32_e32 v126, v174
	v_mov_b32_e32 v127, v100
	v_mov_b32_e32 v124, v178
	v_mov_b32_e32 v125, v92
	v_mov_b32_e32 v100, v175
	v_mov_b32_e32 v92, v179
	v_pk_mul_f32 v[174:175], v[146:147], v[186:187] op_sel_hi:[0,1]
	v_pk_mul_f32 v[178:179], v[146:147], v[190:191] op_sel_hi:[0,1]
	v_pk_mul_f32 v[182:183], v[146:147], v[192:193] op_sel_hi:[0,1]
	v_pk_mul_f32 v[184:185], v[146:147], v[194:195] op_sel_hi:[0,1]
	v_pk_mul_f32 v[186:187], v[146:147], v[196:197] op_sel_hi:[0,1]
	v_pk_mul_f32 v[188:189], v[146:147], v[198:199] op_sel_hi:[0,1]
	v_mul_f32_e32 v137, 0xbfb8aa3b, v172
	v_mul_f32_e32 v146, 0xbfb8aa3b, v176
	v_exp_f32_e32 v137, v137
	v_exp_f32_e32 v146, v146
	v_pk_mul_f32 v[182:183], v[126:127], v[182:183]
	v_pk_mul_f32 v[186:187], v[100:101], v[186:187]
	v_add_f32_e32 v137, 1.0, v137
	v_add_f32_e32 v146, 1.0, v146
	v_rcp_f32_e32 v137, v137
	v_rcp_f32_e32 v146, v146
	v_mul_f32_e32 v159, 0xbfb8aa3b, v182
	v_mul_f32_e32 v135, v172, v173
	v_mul_f32_e32 v157, v176, v177
	v_mul_f32_e32 v163, 0xbfb8aa3b, v186
	v_exp_f32_e32 v159, v159
	v_mul_f32_e32 v135, v135, v137
	v_mul_f32_e32 v137, v157, v146
	v_exp_f32_e32 v146, v163
	v_pk_mul_f32 v[174:175], v[128:129], v[174:175]
	v_add_f32_e32 v159, 1.0, v159
	v_rcp_f32_e32 v159, v159
	v_add_f32_e32 v146, 1.0, v146
	v_mul_f32_e32 v163, 0xbfb8aa3b, v174
	v_rcp_f32_e32 v146, v146
	v_exp_f32_e32 v163, v163
	v_mul_f32_e32 v157, v182, v183
	v_mul_f32_e32 v157, v157, v159
	v_mul_f32_e32 v159, v186, v187
	v_mul_f32_e32 v146, v159, v146
	v_add_f32_e32 v159, 1.0, v163
	v_rcp_f32_e32 v159, v159
	v_pk_mul_f32 v[178:179], v[90:91], v[178:179]
	v_mul_f32_e32 v167, v174, v175
	v_mul_f32_e32 v163, 0xbfb8aa3b, v178
	v_mul_f32_e32 v159, v167, v159
	v_mul_f32_e32 v167, v178, v179
	v_cvt_f32_i32_e32 v179, v110
	v_cvt_f32_i32_e32 v110, v119
	v_exp_f32_e32 v163, v163
	v_pk_mul_f32 v[184:185], v[124:125], v[184:185]
	v_pk_mul_f32 v[188:189], v[92:93], v[188:189]
	v_pk_mul_f32 v[110:111], v[180:181], v[110:111] op_sel_hi:[0,1]
	v_add_f32_e32 v163, 1.0, v163
	v_mul_f32_e32 v172, 0xbfb8aa3b, v184
	v_pk_mul_f32 v[110:111], v[98:99], v[110:111]
	v_rcp_f32_e32 v163, v163
	v_exp_f32_e32 v172, v172
	v_mul_f32_e32 v173, 0xbfb8aa3b, v188
	v_cvt_f32_i32_e32 v119, v112
	v_cvt_f32_i32_e32 v112, v121
	v_mul_f32_e32 v121, 0xbfb8aa3b, v110
	v_exp_f32_e32 v173, v173
	v_exp_f32_e32 v121, v121
	v_mul_f32_e32 v163, v167, v163
; __host__ __device__ __forceinline__ size_t blk_off(int r, int k, int KT) { return ((size_t)((r >> 8) * KT + (k >> 6)) * 256 + (size_t)(r & 255)) * 64 + (size_t)(k & 63); }
; __device__ __forceinline__ unsigned cvt_pk_bf16(float lo, float hi) { unsigned r; asm volatile("v_cvt_pk_bf16_f32 %0, %1, %2" : "=v"(r) : "v"(lo), "v"(hi)); return r; }
; __device__ __forceinline__ float silu_mul(float g, float u) { return g * u * __builtin_amdgcn_rcpf(1.0f + __builtin_amdgcn_exp2f(-g * LOG2E)); }
;     __device__ __forceinline__ void operator()(const i32x4 (&acc)[2][2][4][2], const pg8::Unit& u, int wr, int wc, int fr, int fq) const {
;     ...
;                 const int row = row0 + ai * 128 + m * 16; const float r = rr[ai][m];
;                 f32x4 g0, g1, u0, u1;
; #pragma unroll
;                 for (int e = 0; e < 4; ++e) { g0[e] = (float)acc[ai][0][m][0][e] * r * sg0[e]; g1[e] = (float)acc[ai][0][m][1][e] * r * sg1[e]; u0[e] = (float)acc[ai][1][m][0][e] * r * su0[e]; u1[e] = (float)acc[ai][1][m][1][e] * r * su1[e]; }
;                 float h0 = silu_mul(g0[0], u0[0]), h1 = silu_mul(g0[1], u0[1]), h2 = silu_mul(g0[2], u0[2]), h3 = silu_mul(g0[3], u0[3]);
;                 float h4 = silu_mul(g1[0], u1[0]), h5 = silu_mul(g1[1], u1[1]), h6 = silu_mul(g1[2], u1[2]), h7 = silu_mul(g1[3], u1[3]);
;                 if (ROT) {
;     ...
;                     FW_BF(h0, h1) FW_BF(h2, h3) FW_BF(h4, h5) FW_BF(h6, h7)
;                     FW_BF(h0, h2) FW_BF(h1, h3) FW_BF(h4, h6) FW_BF(h5, h7)
;                     FW_BF(h0, h4) FW_BF(h1, h5) FW_BF(h2, h6) FW_BF(h3, h7)
;     ...
;                     { const bool s16 = (fq & 1) != 0, s32 = (fq & 2) != 0;
;                       FW_X(h0, 16, s16) FW_X(h1, 16, s16) FW_X(h2, 16, s16) FW_X(h3, 16, s16) FW_X(h4, 16, s16) FW_X(h5, 16, s16) FW_X(h6, 16, s16) FW_X(h7, 16, s16)
;                       FW_X(h0, 32, s32) FW_X(h1, 32, s32) FW_X(h2, 32, s32) FW_X(h3, 32, s32) FW_X(h4, 32, s32) FW_X(h5, 32, s32) FW_X(h6, 32, s32) FW_X(h7, 32, s32) }
;     ...
;                     const float sc = 0.17677669529663687f;
;                     h0 *= sc; h1 *= sc; h2 *= sc; h3 *= sc; h4 *= sc; h5 *= sc; h6 *= sc; h7 *= sc;
;                 }
;                 u32x4 w;
;                 w.x = cvt_pk_bf16(h0, h1); w.y = cvt_pk_bf16(h2, h3); w.z = cvt_pk_bf16(h4, h5); w.w = cvt_pk_bf16(h6, h7);
;                 *(u32x4*)(O + blk_off(row, col0, KTF)) = w;
	v_add_f32_e32 v167, 1.0, v172
	v_cvt_f32_i32_e32 v178, v118
	v_cvt_f32_i32_e32 v118, v120
	v_rcp_f32_e32 v167, v167
	v_add_f32_e32 v172, 1.0, v173
	v_add_f32_e32 v121, 1.0, v121
	v_rcp_f32_e32 v172, v172
	v_rcp_f32_e32 v121, v121
	v_mul_f32_e32 v173, v184, v185
	v_pk_mul_f32 v[118:119], v[180:181], v[118:119] op_sel_hi:[0,1]
	v_pk_mul_f32 v[112:113], v[180:181], v[112:113] op_sel_hi:[0,1]
	v_mul_f32_e32 v167, v173, v167
	v_mul_f32_e32 v173, v188, v189
	v_cvt_f32_i32_e32 v183, v106
	v_cvt_f32_i32_e32 v182, v114
	v_pk_mul_f32 v[118:119], v[126:127], v[118:119]
	v_pk_mul_f32 v[112:113], v[100:101], v[112:113]
	v_mul_f32_e32 v110, v110, v111
	v_mul_f32_e32 v175, v173, v172
	v_cvt_pk_bf16_f32 v172, v135, v137
	v_cvt_pk_bf16_f32 v173, v157, v146
	v_and_b32_e32 v146, 0x6780, v123
	v_mul_f32_e32 v110, v110, v121
	v_mul_f32_e32 v111, 0xbfb8aa3b, v118
	v_mul_f32_e32 v121, 0xbfb8aa3b, v112
	v_lshl_add_u64 v[176:177], s[18:19], 0, v[146:147]
	v_mov_b32_e32 v157, v147
	v_exp_f32_e32 v111, v111
	v_exp_f32_e32 v121, v121
	v_cvt_pk_bf16_f32 v174, v159, v163
	v_cvt_pk_bf16_f32 v175, v167, v175
	v_lshl_add_u64 v[176:177], v[176:177], 0, v[156:157]
	global_store_dwordx4 v[176:177], v[172:175], off nt
	v_cvt_f32_i32_e32 v106, v115
	v_mul_f32_e32 v118, v118, v119
	v_pk_mul_f32 v[174:175], v[180:181], v[182:183] op_sel_hi:[0,1]
	v_pk_mul_f32 v[114:115], v[128:129], v[174:175]
	v_add_f32_e32 v111, 1.0, v111
	v_add_f32_e32 v119, 1.0, v121
	v_mul_f32_e32 v121, 0xbfb8aa3b, v114
	v_rcp_f32_e32 v111, v111
	v_exp_f32_e32 v121, v121
	v_pk_mul_f32 v[106:107], v[180:181], v[106:107] op_sel_hi:[0,1]
	v_cvt_f32_i32_e32 v175, v108
	v_cvt_f32_i32_e32 v174, v116
	v_pk_mul_f32 v[106:107], v[90:91], v[106:107]
	v_cvt_f32_i32_e32 v108, v117
	v_mul_f32_e32 v111, v118, v111
	v_mul_f32_e32 v112, v112, v113
	v_add_f32_e32 v113, 1.0, v121
	v_mul_f32_e32 v118, 0xbfb8aa3b, v106
	v_rcp_f32_e32 v113, v113
	v_exp_f32_e32 v118, v118
	v_pk_mul_f32 v[174:175], v[180:181], v[174:175] op_sel_hi:[0,1]
	v_pk_mul_f32 v[172:173], v[180:181], v[178:179] op_sel_hi:[0,1]
	v_pk_mul_f32 v[116:117], v[124:125], v[174:175]
	v_pk_mul_f32 v[108:109], v[180:181], v[108:109] op_sel_hi:[0,1]
	v_mul_f32_e32 v114, v114, v115
	v_pk_mul_f32 v[172:173], v[130:131], v[172:173]
	v_pk_mul_f32 v[108:109], v[92:93], v[108:109]
	v_mul_f32_e32 v113, v114, v113
	v_mul_f32_e32 v106, v106, v107
	v_add_f32_e32 v107, 1.0, v118
	v_mul_f32_e32 v114, 0xbfb8aa3b, v116
	v_mul_f32_e32 v120, 0xbfb8aa3b, v172
	v_rcp_f32_e32 v107, v107
	v_exp_f32_e32 v114, v114
	v_mul_f32_e32 v115, 0xbfb8aa3b, v108
	v_exp_f32_e32 v120, v120
	v_exp_f32_e32 v115, v115
	v_mul_f32_e32 v118, v106, v107
	v_add_f32_e32 v106, 1.0, v114
	v_add_f32_e32 v120, 1.0, v120
	v_rcp_f32_e32 v106, v106
	v_add_f32_e32 v107, 1.0, v115
	v_rcp_f32_e32 v120, v120
	v_rcp_f32_e32 v119, v119
	v_rcp_f32_e32 v107, v107
	v_mul_f32_e32 v114, v116, v117
	v_mul_f32_e32 v135, v172, v173
	v_mul_f32_e32 v114, v114, v106
	v_mul_f32_e32 v106, v108, v109
	v_mul_f32_e32 v120, v135, v120
	v_mul_f32_e32 v112, v112, v119
	v_mul_f32_e32 v109, v106, v107
	v_cvt_pk_bf16_f32 v106, v120, v110
	v_cvt_pk_bf16_f32 v107, v111, v112
	v_cvt_pk_bf16_f32 v108, v113, v118
	v_cvt_f32_i32_e32 v113, v86
	v_cvt_f32_i32_e32 v86, v103
	v_cvt_f32_i32_e32 v103, v88
	v_cvt_f32_i32_e32 v88, v105
	v_cvt_f32_i32_e32 v112, v102
	v_pk_mul_f32 v[86:87], v[164:165], v[86:87] op_sel_hi:[0,1]
	v_pk_mul_f32 v[86:87], v[98:99], v[86:87]
	v_cvt_f32_i32_e32 v102, v104
	v_mul_f32_e32 v105, 0xbfb8aa3b, v86
	v_exp_f32_e32 v105, v105
	v_pk_mul_f32 v[88:89], v[164:165], v[88:89] op_sel_hi:[0,1]
	v_pk_mul_f32 v[102:103], v[164:165], v[102:103] op_sel_hi:[0,1]
	v_cvt_pk_bf16_f32 v109, v114, v109
	v_add_f32_e32 v105, 1.0, v105
	v_rcp_f32_e32 v105, v105
	v_lshlrev_b32_e32 v110, 7, v166
	v_cvt_f32_i32_e32 v115, v82
	v_cvt_f32_i32_e32 v114, v94
	v_pk_mul_f32 v[102:103], v[126:127], v[102:103]
	v_pk_mul_f32 v[88:89], v[100:101], v[88:89]
	v_mul_f32_e32 v86, v86, v87
	v_and_b32_e32 v146, 0x6f80, v110
	v_mul_f32_e32 v86, v86, v105
	v_mul_f32_e32 v87, 0xbfb8aa3b, v102
	v_mul_f32_e32 v105, 0xbfb8aa3b, v88
	v_lshl_add_u64 v[110:111], s[18:19], 0, v[146:147]
	v_exp_f32_e32 v87, v87
	v_exp_f32_e32 v105, v105
	v_lshl_add_u64 v[110:111], v[110:111], 0, v[156:157]
	global_store_dwordx4 v[110:111], v[106:109], off nt
	v_cvt_f32_i32_e32 v82, v95
	v_mul_f32_e32 v102, v102, v103
	v_pk_mul_f32 v[108:109], v[164:165], v[114:115] op_sel_hi:[0,1]
	v_pk_mul_f32 v[94:95], v[128:129], v[108:109]
	v_add_f32_e32 v87, 1.0, v87
	v_add_f32_e32 v103, 1.0, v105
	v_mul_f32_e32 v105, 0xbfb8aa3b, v94
	v_rcp_f32_e32 v87, v87
	v_exp_f32_e32 v105, v105
	v_pk_mul_f32 v[82:83], v[164:165], v[82:83] op_sel_hi:[0,1]
	v_cvt_f32_i32_e32 v109, v84
	v_cvt_f32_i32_e32 v108, v96
	v_pk_mul_f32 v[82:83], v[90:91], v[82:83]
	v_cvt_f32_i32_e32 v84, v97
	v_mul_f32_e32 v87, v102, v87
	v_mul_f32_e32 v88, v88, v89
	v_add_f32_e32 v89, 1.0, v105
	v_mul_f32_e32 v102, 0xbfb8aa3b, v82
	v_rcp_f32_e32 v89, v89
	v_exp_f32_e32 v102, v102
	v_pk_mul_f32 v[108:109], v[164:165], v[108:109] op_sel_hi:[0,1]
	v_pk_mul_f32 v[106:107], v[164:165], v[112:113] op_sel_hi:[0,1]
	v_pk_mul_f32 v[96:97], v[124:125], v[108:109]
	v_pk_mul_f32 v[84:85], v[164:165], v[84:85] op_sel_hi:[0,1]
	v_mul_f32_e32 v94, v94, v95
	v_pk_mul_f32 v[106:107], v[130:131], v[106:107]
	v_pk_mul_f32 v[84:85], v[92:93], v[84:85]
	v_mul_f32_e32 v89, v94, v89
	v_mul_f32_e32 v82, v82, v83
	v_add_f32_e32 v83, 1.0, v102
	v_mul_f32_e32 v94, 0xbfb8aa3b, v96
	v_mul_f32_e32 v104, 0xbfb8aa3b, v106
	v_rcp_f32_e32 v83, v83
	v_exp_f32_e32 v94, v94
	v_mul_f32_e32 v95, 0xbfb8aa3b, v84
	v_exp_f32_e32 v104, v104
	v_exp_f32_e32 v95, v95
; __host__ __device__ __forceinline__ size_t blk_off(int r, int k, int KT) { return ((size_t)((r >> 8) * KT + (k >> 6)) * 256 + (size_t)(r & 255)) * 64 + (size_t)(k & 63); }
; __device__ __forceinline__ unsigned cvt_pk_bf16(float lo, float hi) { unsigned r; asm volatile("v_cvt_pk_bf16_f32 %0, %1, %2" : "=v"(r) : "v"(lo), "v"(hi)); return r; }
; __device__ __forceinline__ float silu_mul(float g, float u) { return g * u * __builtin_amdgcn_rcpf(1.0f + __builtin_amdgcn_exp2f(-g * LOG2E)); }
;     __device__ __forceinline__ void operator()(const i32x4 (&acc)[2][2][4][2], const pg8::Unit& u, int wr, int wc, int fr, int fq) const {
;     ...
;                 const int row = row0 + ai * 128 + m * 16; const float r = rr[ai][m];
;                 f32x4 g0, g1, u0, u1;
; #pragma unroll
;                 for (int e = 0; e < 4; ++e) { g0[e] = (float)acc[ai][0][m][0][e] * r * sg0[e]; g1[e] = (float)acc[ai][0][m][1][e] * r * sg1[e]; u0[e] = (float)acc[ai][1][m][0][e] * r * su0[e]; u1[e] = (float)acc[ai][1][m][1][e] * r * su1[e]; }
;                 float h0 = silu_mul(g0[0], u0[0]), h1 = silu_mul(g0[1], u0[1]), h2 = silu_mul(g0[2], u0[2]), h3 = silu_mul(g0[3], u0[3]);
;                 float h4 = silu_mul(g1[0], u1[0]), h5 = silu_mul(g1[1], u1[1]), h6 = silu_mul(g1[2], u1[2]), h7 = silu_mul(g1[3], u1[3]);
;                 if (ROT) {
;     ...
;                     FW_BF(h0, h1) FW_BF(h2, h3) FW_BF(h4, h5) FW_BF(h6, h7)
;                     FW_BF(h0, h2) FW_BF(h1, h3) FW_BF(h4, h6) FW_BF(h5, h7)
;                     FW_BF(h0, h4) FW_BF(h1, h5) FW_BF(h2, h6) FW_BF(h3, h7)
;     ...
;                     { const bool s16 = (fq & 1) != 0, s32 = (fq & 2) != 0;
;                       FW_X(h0, 16, s16) FW_X(h1, 16, s16) FW_X(h2, 16, s16) FW_X(h3, 16, s16) FW_X(h4, 16, s16) FW_X(h5, 16, s16) FW_X(h6, 16, s16) FW_X(h7, 16, s16)
;                       FW_X(h0, 32, s32) FW_X(h1, 32, s32) FW_X(h2, 32, s32) FW_X(h3, 32, s32) FW_X(h4, 32, s32) FW_X(h5, 32, s32) FW_X(h6, 32, s32) FW_X(h7, 32, s32) }
;     ...
;                     const float sc = 0.17677669529663687f;
;                     h0 *= sc; h1 *= sc; h2 *= sc; h3 *= sc; h4 *= sc; h5 *= sc; h6 *= sc; h7 *= sc;
;                 }
;                 u32x4 w;
;                 w.x = cvt_pk_bf16(h0, h1); w.y = cvt_pk_bf16(h2, h3); w.z = cvt_pk_bf16(h4, h5); w.w = cvt_pk_bf16(h6, h7);
;                 *(u32x4*)(O + blk_off(row, col0, KTF)) = w;
	v_mul_f32_e32 v102, v82, v83
	v_add_f32_e32 v82, 1.0, v94
	v_add_f32_e32 v104, 1.0, v104
	v_rcp_f32_e32 v82, v82
	v_add_f32_e32 v83, 1.0, v95
	v_rcp_f32_e32 v104, v104
	v_rcp_f32_e32 v103, v103
	v_rcp_f32_e32 v83, v83
	v_mul_f32_e32 v94, v96, v97
	v_mul_f32_e32 v106, v106, v107
	v_mul_f32_e32 v94, v94, v82
	v_mul_f32_e32 v82, v84, v85
	v_mul_f32_e32 v104, v106, v104
	v_mul_f32_e32 v88, v88, v103
	v_mul_f32_e32 v85, v82, v83
	v_cvt_pk_bf16_f32 v82, v104, v86
	v_cvt_pk_bf16_f32 v83, v87, v88
	v_cvt_pk_bf16_f32 v84, v89, v102
	v_cvt_f32_i32_e32 v89, v70
	v_cvt_f32_i32_e32 v70, v79
	v_cvt_f32_i32_e32 v79, v72
	v_cvt_f32_i32_e32 v72, v81
	v_cvt_f32_i32_e32 v88, v78
	v_pk_mul_f32 v[70:71], v[160:161], v[70:71] op_sel_hi:[0,1]
	v_pk_mul_f32 v[70:71], v[98:99], v[70:71]
	v_cvt_f32_i32_e32 v78, v80
	v_mul_f32_e32 v81, 0xbfb8aa3b, v70
	v_exp_f32_e32 v81, v81
	v_pk_mul_f32 v[72:73], v[160:161], v[72:73] op_sel_hi:[0,1]
	v_pk_mul_f32 v[78:79], v[160:161], v[78:79] op_sel_hi:[0,1]
	v_cvt_pk_bf16_f32 v85, v94, v85
	v_add_f32_e32 v81, 1.0, v81
	v_rcp_f32_e32 v81, v81
	v_lshlrev_b32_e32 v86, 7, v162
	v_cvt_f32_i32_e32 v95, v66
	v_cvt_f32_i32_e32 v94, v74
	v_pk_mul_f32 v[78:79], v[126:127], v[78:79]
	v_pk_mul_f32 v[72:73], v[100:101], v[72:73]
	v_mul_f32_e32 v70, v70, v71
	v_and_b32_e32 v146, 0x7780, v86
	v_mul_f32_e32 v70, v70, v81
	v_mul_f32_e32 v71, 0xbfb8aa3b, v78
	v_mul_f32_e32 v81, 0xbfb8aa3b, v72
	v_lshl_add_u64 v[86:87], s[18:19], 0, v[146:147]
	v_exp_f32_e32 v71, v71
	v_exp_f32_e32 v81, v81
	v_lshl_add_u64 v[86:87], v[86:87], 0, v[156:157]
	global_store_dwordx4 v[86:87], v[82:85], off nt
	v_cvt_f32_i32_e32 v66, v75
	v_mul_f32_e32 v78, v78, v79
	v_pk_mul_f32 v[84:85], v[160:161], v[94:95] op_sel_hi:[0,1]
	v_pk_mul_f32 v[74:75], v[128:129], v[84:85]
	v_add_f32_e32 v71, 1.0, v71
	v_add_f32_e32 v79, 1.0, v81
	v_mul_f32_e32 v81, 0xbfb8aa3b, v74
	v_rcp_f32_e32 v71, v71
	v_exp_f32_e32 v81, v81
	v_pk_mul_f32 v[66:67], v[160:161], v[66:67] op_sel_hi:[0,1]
	v_cvt_f32_i32_e32 v85, v68
	v_cvt_f32_i32_e32 v84, v76
	v_pk_mul_f32 v[66:67], v[90:91], v[66:67]
	v_cvt_f32_i32_e32 v68, v77
	v_mul_f32_e32 v71, v78, v71
	v_mul_f32_e32 v72, v72, v73
	v_add_f32_e32 v73, 1.0, v81
	v_mul_f32_e32 v78, 0xbfb8aa3b, v66
	v_rcp_f32_e32 v73, v73
	v_exp_f32_e32 v78, v78
	v_pk_mul_f32 v[84:85], v[160:161], v[84:85] op_sel_hi:[0,1]
	v_pk_mul_f32 v[82:83], v[160:161], v[88:89] op_sel_hi:[0,1]
	v_pk_mul_f32 v[76:77], v[124:125], v[84:85]
	v_pk_mul_f32 v[68:69], v[160:161], v[68:69] op_sel_hi:[0,1]
	v_mul_f32_e32 v74, v74, v75
	v_pk_mul_f32 v[82:83], v[130:131], v[82:83]
	v_pk_mul_f32 v[68:69], v[92:93], v[68:69]
	v_mul_f32_e32 v73, v74, v73
	v_mul_f32_e32 v66, v66, v67
	v_add_f32_e32 v67, 1.0, v78
	v_mul_f32_e32 v74, 0xbfb8aa3b, v76
	v_mul_f32_e32 v80, 0xbfb8aa3b, v82
	v_rcp_f32_e32 v67, v67
	v_exp_f32_e32 v74, v74
	v_mul_f32_e32 v75, 0xbfb8aa3b, v68
	v_exp_f32_e32 v80, v80
	v_exp_f32_e32 v75, v75
	v_mul_f32_e32 v78, v66, v67
	v_add_f32_e32 v66, 1.0, v74
	v_add_f32_e32 v80, 1.0, v80
	v_rcp_f32_e32 v66, v66
	v_add_f32_e32 v67, 1.0, v75
	v_rcp_f32_e32 v80, v80
	v_rcp_f32_e32 v67, v67
	v_rcp_f32_e32 v79, v79
	v_mul_f32_e32 v74, v76, v77
	v_mul_f32_e32 v82, v82, v83
	v_mul_f32_e32 v74, v74, v66
	v_mul_f32_e32 v66, v68, v69
	v_mul_f32_e32 v80, v82, v80
	v_mul_f32_e32 v69, v66, v67
	v_cvt_pk_bf16_f32 v66, v80, v70
	v_lshlrev_b32_e32 v70, 7, v158
	v_and_b32_e32 v146, 0x7f80, v70
	v_mul_f32_e32 v72, v72, v79
	v_cvt_pk_bf16_f32 v67, v71, v72
	v_lshl_add_u64 v[70:71], s[18:19], 0, v[146:147]
	v_cvt_pk_bf16_f32 v68, v73, v78
	v_cvt_pk_bf16_f32 v69, v74, v69
	v_lshl_add_u64 v[70:71], v[70:71], 0, v[156:157]
	global_store_dwordx4 v[70:71], v[66:69], off nt
	v_cvt_f32_i32_e32 v71, v50
	v_cvt_f32_i32_e32 v70, v58
	v_cvt_f32_i32_e32 v69, v54
	v_cvt_f32_i32_e32 v54, v63
	v_cvt_f32_i32_e32 v63, v56
	v_cvt_f32_i32_e32 v56, v65
	v_cvt_f32_i32_e32 v68, v62
	v_pk_mul_f32 v[54:55], v[136:137], v[54:55] op_sel_hi:[0,1]
	v_pk_mul_f32 v[54:55], v[98:99], v[54:55]
	v_cvt_f32_i32_e32 v62, v64
	v_mul_f32_e32 v65, 0xbfb8aa3b, v54
	v_exp_f32_e32 v65, v65
	v_pk_mul_f32 v[56:57], v[136:137], v[56:57] op_sel_hi:[0,1]
	v_pk_mul_f32 v[62:63], v[136:137], v[62:63] op_sel_hi:[0,1]
	v_pk_mul_f32 v[62:63], v[126:127], v[62:63]
	v_add_f32_e32 v65, 1.0, v65
	v_rcp_f32_e32 v65, v65
	v_pk_mul_f32 v[56:57], v[100:101], v[56:57]
	v_mul_f32_e32 v54, v54, v55
	v_mul_f32_e32 v55, 0xbfb8aa3b, v62
	v_mul_f32_e32 v54, v54, v65
	v_mul_f32_e32 v65, 0xbfb8aa3b, v56
	v_exp_f32_e32 v55, v55
	v_exp_f32_e32 v65, v65
	v_pk_mul_f32 v[70:71], v[136:137], v[70:71] op_sel_hi:[0,1]
	v_cvt_f32_i32_e32 v50, v59
	v_pk_mul_f32 v[58:59], v[128:129], v[70:71]
	v_mul_f32_e32 v62, v62, v63
	v_add_f32_e32 v55, 1.0, v55
	v_add_f32_e32 v63, 1.0, v65
	v_mul_f32_e32 v65, 0xbfb8aa3b, v58
	v_rcp_f32_e32 v55, v55
	v_exp_f32_e32 v65, v65
	v_pk_mul_f32 v[50:51], v[136:137], v[50:51] op_sel_hi:[0,1]
	v_cvt_f32_i32_e32 v71, v52
	v_cvt_f32_i32_e32 v70, v60
	v_pk_mul_f32 v[50:51], v[90:91], v[50:51]
	v_mul_f32_e32 v55, v62, v55
	v_mul_f32_e32 v56, v56, v57
	v_add_f32_e32 v57, 1.0, v65
	v_mul_f32_e32 v62, 0xbfb8aa3b, v50
	v_rcp_f32_e32 v57, v57
	v_exp_f32_e32 v62, v62
	v_pk_mul_f32 v[70:71], v[136:137], v[70:71] op_sel_hi:[0,1]
	v_cvt_f32_i32_e32 v52, v61
	v_pk_mul_f32 v[60:61], v[124:125], v[70:71]
	v_mul_f32_e32 v58, v58, v59
	v_mul_f32_e32 v57, v58, v57
	v_mul_f32_e32 v50, v50, v51
	v_add_f32_e32 v51, 1.0, v62
	v_mul_f32_e32 v58, 0xbfb8aa3b, v60
	v_rcp_f32_e32 v51, v51
	v_exp_f32_e32 v58, v58
	v_pk_mul_f32 v[52:53], v[136:137], v[52:53] op_sel_hi:[0,1]
	v_pk_mul_f32 v[52:53], v[92:93], v[52:53]
	v_mul_f32_e32 v50, v50, v51
	v_mul_f32_e32 v59, 0xbfb8aa3b, v52
; __host__ __device__ __forceinline__ size_t blk_off(int r, int k, int KT) { return ((size_t)((r >> 8) * KT + (k >> 6)) * 256 + (size_t)(r & 255)) * 64 + (size_t)(k & 63); }
; __device__ __forceinline__ unsigned cvt_pk_bf16(float lo, float hi) { unsigned r; asm volatile("v_cvt_pk_bf16_f32 %0, %1, %2" : "=v"(r) : "v"(lo), "v"(hi)); return r; }
; __device__ __forceinline__ float silu_mul(float g, float u) { return g * u * __builtin_amdgcn_rcpf(1.0f + __builtin_amdgcn_exp2f(-g * LOG2E)); }
;     __device__ __forceinline__ void operator()(const i32x4 (&acc)[2][2][4][2], const pg8::Unit& u, int wr, int wc, int fr, int fq) const {
;     ...
;                 const int row = row0 + ai * 128 + m * 16; const float r = rr[ai][m];
;                 f32x4 g0, g1, u0, u1;
; #pragma unroll
;                 for (int e = 0; e < 4; ++e) { g0[e] = (float)acc[ai][0][m][0][e] * r * sg0[e]; g1[e] = (float)acc[ai][0][m][1][e] * r * sg1[e]; u0[e] = (float)acc[ai][1][m][0][e] * r * su0[e]; u1[e] = (float)acc[ai][1][m][1][e] * r * su1[e]; }
;                 float h0 = silu_mul(g0[0], u0[0]), h1 = silu_mul(g0[1], u0[1]), h2 = silu_mul(g0[2], u0[2]), h3 = silu_mul(g0[3], u0[3]);
;                 float h4 = silu_mul(g1[0], u1[0]), h5 = silu_mul(g1[1], u1[1]), h6 = silu_mul(g1[2], u1[2]), h7 = silu_mul(g1[3], u1[3]);
;                 if (ROT) {
;     ...
;                     FW_BF(h0, h1) FW_BF(h2, h3) FW_BF(h4, h5) FW_BF(h6, h7)
;                     FW_BF(h0, h2) FW_BF(h1, h3) FW_BF(h4, h6) FW_BF(h5, h7)
;                     FW_BF(h0, h4) FW_BF(h1, h5) FW_BF(h2, h6) FW_BF(h3, h7)
;     ...
;                     { const bool s16 = (fq & 1) != 0, s32 = (fq & 2) != 0;
;                       FW_X(h0, 16, s16) FW_X(h1, 16, s16) FW_X(h2, 16, s16) FW_X(h3, 16, s16) FW_X(h4, 16, s16) FW_X(h5, 16, s16) FW_X(h6, 16, s16) FW_X(h7, 16, s16)
;                       FW_X(h0, 32, s32) FW_X(h1, 32, s32) FW_X(h2, 32, s32) FW_X(h3, 32, s32) FW_X(h4, 32, s32) FW_X(h5, 32, s32) FW_X(h6, 32, s32) FW_X(h7, 32, s32) }
;     ...
;                     const float sc = 0.17677669529663687f;
;                     h0 *= sc; h1 *= sc; h2 *= sc; h3 *= sc; h4 *= sc; h5 *= sc; h6 *= sc; h7 *= sc;
;                 }
;                 u32x4 w;
;                 w.x = cvt_pk_bf16(h0, h1); w.y = cvt_pk_bf16(h2, h3); w.z = cvt_pk_bf16(h4, h5); w.w = cvt_pk_bf16(h6, h7);
;                 *(u32x4*)(O + blk_off(row, col0, KTF)) = w;
	v_exp_f32_e32 v59, v59
	v_add_f32_e32 v51, 1.0, v58
	v_rcp_f32_e32 v51, v51
	v_pk_mul_f32 v[68:69], v[136:137], v[68:69] op_sel_hi:[0,1]
	v_pk_mul_f32 v[68:69], v[130:131], v[68:69]
	v_add_f32_e32 v58, 1.0, v59
	v_mul_f32_e32 v59, v60, v61
	v_mul_f32_e32 v64, 0xbfb8aa3b, v68
	v_mul_f32_e32 v51, v59, v51
	v_cvt_f32_i32_e32 v59, v38
	v_cvt_f32_i32_e32 v38, v47
	v_exp_f32_e32 v64, v64
	v_rcp_f32_e32 v58, v58
	v_rcp_f32_e32 v63, v63
	v_pk_mul_f32 v[38:39], v[134:135], v[38:39] op_sel_hi:[0,1]
	v_add_f32_e32 v64, 1.0, v64
	v_pk_mul_f32 v[38:39], v[98:99], v[38:39]
	v_rcp_f32_e32 v64, v64
	v_cvt_f32_i32_e32 v47, v40
	v_cvt_f32_i32_e32 v40, v49
	v_mul_f32_e32 v49, 0xbfb8aa3b, v38
	v_exp_f32_e32 v49, v49
	v_mul_f32_e32 v52, v52, v53
	v_mul_f32_e32 v68, v68, v69
	v_mul_f32_e32 v58, v52, v58
	v_mul_f32_e32 v64, v68, v64
	v_mul_f32_e32 v56, v56, v63
	v_cvt_pk_bf16_f32 v52, v64, v54
	v_cvt_pk_bf16_f32 v53, v55, v56
	v_cvt_pk_bf16_f32 v54, v57, v50
	v_cvt_pk_bf16_f32 v55, v51, v58
	v_cvt_f32_i32_e32 v58, v46
	v_cvt_f32_i32_e32 v46, v48
	v_add_f32_e32 v49, 1.0, v49
	v_lshrrev_b32_e32 v66, 8, v133
	v_mov_b32_e32 v67, s11
	v_rcp_f32_e32 v49, v49
	v_mad_i32_i24 v66, v66, s48, v67
	v_ashrrev_i32_e32 v67, 31, v66
	v_pk_mul_f32 v[46:47], v[134:135], v[46:47] op_sel_hi:[0,1]
	v_pk_mul_f32 v[40:41], v[134:135], v[40:41] op_sel_hi:[0,1]
	v_lshlrev_b64 v[66:67], 15, v[66:67]
	v_lshlrev_b32_e32 v56, 7, v133
	v_cvt_f32_i32_e32 v61, v34
	v_cvt_f32_i32_e32 v60, v42
	v_pk_mul_f32 v[46:47], v[126:127], v[46:47]
	v_pk_mul_f32 v[40:41], v[100:101], v[40:41]
	v_mul_f32_e32 v38, v38, v39
	v_lshl_add_u64 v[50:51], s[84:85], 0, v[66:67]
	v_and_b32_e32 v146, 0x6780, v56
	v_mul_f32_e32 v38, v38, v49
	v_mul_f32_e32 v39, 0xbfb8aa3b, v46
	v_mul_f32_e32 v49, 0xbfb8aa3b, v40
	v_lshl_add_u64 v[56:57], v[50:51], 0, v[146:147]
	v_exp_f32_e32 v39, v39
	v_exp_f32_e32 v49, v49
	v_lshl_add_u64 v[56:57], v[56:57], 0, v[156:157]
	global_store_dwordx4 v[56:57], v[52:55], off nt
	v_cvt_f32_i32_e32 v34, v43
	v_mul_f32_e32 v46, v46, v47
	v_pk_mul_f32 v[54:55], v[134:135], v[60:61] op_sel_hi:[0,1]
	v_pk_mul_f32 v[42:43], v[128:129], v[54:55]
	v_add_f32_e32 v39, 1.0, v39
	v_add_f32_e32 v47, 1.0, v49
	v_mul_f32_e32 v49, 0xbfb8aa3b, v42
	v_rcp_f32_e32 v39, v39
	v_exp_f32_e32 v49, v49
	v_pk_mul_f32 v[34:35], v[134:135], v[34:35] op_sel_hi:[0,1]
	v_cvt_f32_i32_e32 v55, v36
	v_cvt_f32_i32_e32 v54, v44
	v_pk_mul_f32 v[34:35], v[90:91], v[34:35]
	v_cvt_f32_i32_e32 v36, v45
	v_mul_f32_e32 v39, v46, v39
	v_mul_f32_e32 v40, v40, v41
	v_add_f32_e32 v41, 1.0, v49
	v_mul_f32_e32 v46, 0xbfb8aa3b, v34
	v_rcp_f32_e32 v41, v41
	v_exp_f32_e32 v46, v46
	v_pk_mul_f32 v[54:55], v[134:135], v[54:55] op_sel_hi:[0,1]
	v_pk_mul_f32 v[52:53], v[134:135], v[58:59] op_sel_hi:[0,1]
	v_pk_mul_f32 v[44:45], v[124:125], v[54:55]
	v_pk_mul_f32 v[36:37], v[134:135], v[36:37] op_sel_hi:[0,1]
	v_mul_f32_e32 v42, v42, v43
	v_pk_mul_f32 v[52:53], v[130:131], v[52:53]
	v_pk_mul_f32 v[36:37], v[92:93], v[36:37]
	v_mul_f32_e32 v41, v42, v41
	v_mul_f32_e32 v34, v34, v35
	v_add_f32_e32 v35, 1.0, v46
	v_mul_f32_e32 v42, 0xbfb8aa3b, v44
	v_mul_f32_e32 v48, 0xbfb8aa3b, v52
	v_rcp_f32_e32 v35, v35
	v_exp_f32_e32 v42, v42
	v_mul_f32_e32 v43, 0xbfb8aa3b, v36
	v_exp_f32_e32 v48, v48
	v_exp_f32_e32 v43, v43
	v_mul_f32_e32 v46, v34, v35
	v_add_f32_e32 v34, 1.0, v42
	v_add_f32_e32 v48, 1.0, v48
	v_rcp_f32_e32 v34, v34
	v_add_f32_e32 v35, 1.0, v43
	v_rcp_f32_e32 v48, v48
	v_rcp_f32_e32 v47, v47
	v_rcp_f32_e32 v35, v35
	v_mul_f32_e32 v42, v44, v45
	v_mul_f32_e32 v52, v52, v53
	v_mul_f32_e32 v42, v42, v34
	v_mul_f32_e32 v34, v36, v37
	v_mul_f32_e32 v48, v52, v48
	v_mul_f32_e32 v40, v40, v47
	v_mul_f32_e32 v37, v34, v35
	v_cvt_pk_bf16_f32 v34, v48, v38
	v_cvt_pk_bf16_f32 v35, v39, v40
	v_cvt_pk_bf16_f32 v36, v41, v46
	v_cvt_f32_i32_e32 v41, v22
	v_cvt_f32_i32_e32 v22, v31
	v_cvt_f32_i32_e32 v31, v24
	v_cvt_f32_i32_e32 v24, v33
	v_cvt_f32_i32_e32 v40, v30
	v_pk_mul_f32 v[22:23], v[132:133], v[22:23] op_sel_hi:[0,1]
	v_pk_mul_f32 v[22:23], v[98:99], v[22:23]
	v_cvt_f32_i32_e32 v30, v32
	v_mul_f32_e32 v33, 0xbfb8aa3b, v22
	v_exp_f32_e32 v33, v33
	v_pk_mul_f32 v[24:25], v[132:133], v[24:25] op_sel_hi:[0,1]
	v_pk_mul_f32 v[30:31], v[132:133], v[30:31] op_sel_hi:[0,1]
	v_cvt_pk_bf16_f32 v37, v42, v37
	v_add_f32_e32 v33, 1.0, v33
	v_rcp_f32_e32 v33, v33
	v_add_u32_e32 v38, 0x4800, v123
	v_cvt_f32_i32_e32 v43, v18
	v_cvt_f32_i32_e32 v42, v26
	v_pk_mul_f32 v[30:31], v[126:127], v[30:31]
	v_pk_mul_f32 v[24:25], v[100:101], v[24:25]
	v_mul_f32_e32 v22, v22, v23
	v_and_b32_e32 v146, 0x6f80, v38
	v_mul_f32_e32 v22, v22, v33
	v_mul_f32_e32 v23, 0xbfb8aa3b, v30
	v_mul_f32_e32 v33, 0xbfb8aa3b, v24
	v_lshl_add_u64 v[38:39], v[50:51], 0, v[146:147]
	v_exp_f32_e32 v23, v23
	v_exp_f32_e32 v33, v33
	v_lshl_add_u64 v[38:39], v[38:39], 0, v[156:157]
	global_store_dwordx4 v[38:39], v[34:37], off nt
	v_cvt_f32_i32_e32 v18, v27
	v_mul_f32_e32 v30, v30, v31
; #define PG8_BAR __builtin_amdgcn_s_barrier()
; template <class Epi, class Sched, bool I8 = false>
; __device__ __forceinline__ void gemm_phase(LAS unsigned char* lds, const Gemm g, const Sched& S, const Epi& E) {
;     ...
;         if (wr == 0) PG8_BAR;
;         E(acc, cur, wr, wc, fr, fq);
;         if (!has_next) break;
; #pragma unroll
;         for (int a = 0; a < 2; ++a)
; #pragma unroll
;             for (int b = 0; b < 2; ++b)
; #pragma unroll
;                 for (int m = 0; m < 4; ++m)
; #pragma unroll
;     __device__ __forceinline__ void operator()(const i32x4 (&acc)[2][2][4][2], const pg8::Unit& u, int wr, int wc, int fr, int fq) const {
;     ...
;                 const int row = row0 + ai * 128 + m * 16; const float r = rr[ai][m];
;                 f32x4 g0, g1, u0, u1;
; #pragma unroll
;                 for (int e = 0; e < 4; ++e) { g0[e] = (float)acc[ai][0][m][0][e] * r * sg0[e]; g1[e] = (float)acc[ai][0][m][1][e] * r * sg1[e]; u0[e] = (float)acc[ai][1][m][0][e] * r * su0[e]; u1[e] = (float)acc[ai][1][m][1][e] * r * su1[e]; }
;                 float h0 = silu_mul(g0[0], u0[0]), h1 = silu_mul(g0[1], u0[1]), h2 = silu_mul(g0[2], u0[2]), h3 = silu_mul(g0[3], u0[3]);
;                 float h4 = silu_mul(g1[0], u1[0]), h5 = silu_mul(g1[1], u1[1]), h6 = silu_mul(g1[2], u1[2]), h7 = silu_mul(g1[3], u1[3]);
;                 if (ROT) {
;     ...
;                     FW_BF(h0, h1) FW_BF(h2, h3) FW_BF(h4, h5) FW_BF(h6, h7)
;                     FW_BF(h0, h2) FW_BF(h1, h3) FW_BF(h4, h6) FW_BF(h5, h7)
;                     FW_BF(h0, h4) FW_BF(h1, h5) FW_BF(h2, h6) FW_BF(h3, h7)
;     ...
;                     { const bool s16 = (fq & 1) != 0, s32 = (fq & 2) != 0;
;                       FW_X(h0, 16, s16) FW_X(h1, 16, s16) FW_X(h2, 16, s16) FW_X(h3, 16, s16) FW_X(h4, 16, s16) FW_X(h5, 16, s16) FW_X(h6, 16, s16) FW_X(h7, 16, s16)
;                       FW_X(h0, 32, s32) FW_X(h1, 32, s32) FW_X(h2, 32, s32) FW_X(h3, 32, s32) FW_X(h4, 32, s32) FW_X(h5, 32, s32) FW_X(h6, 32, s32) FW_X(h7, 32, s32) }
;     ...
;                     const float sc = 0.17677669529663687f;
;                     h0 *= sc; h1 *= sc; h2 *= sc; h3 *= sc; h4 *= sc; h5 *= sc; h6 *= sc; h7 *= sc;
;                 }
;                 u32x4 w;
;                 w.x = cvt_pk_bf16(h0, h1); w.y = cvt_pk_bf16(h2, h3); w.z = cvt_pk_bf16(h4, h5); w.w = cvt_pk_bf16(h6, h7);
;                 *(u32x4*)(O + blk_off(row, col0, KTF)) = w;
	v_pk_mul_f32 v[36:37], v[132:133], v[42:43] op_sel_hi:[0,1]
	v_pk_mul_f32 v[26:27], v[128:129], v[36:37]
	v_add_f32_e32 v23, 1.0, v23
	v_add_f32_e32 v31, 1.0, v33
	v_mul_f32_e32 v33, 0xbfb8aa3b, v26
	v_rcp_f32_e32 v23, v23
	v_exp_f32_e32 v33, v33
	v_pk_mul_f32 v[18:19], v[132:133], v[18:19] op_sel_hi:[0,1]
	v_cvt_f32_i32_e32 v37, v20
	v_cvt_f32_i32_e32 v36, v28
	v_pk_mul_f32 v[18:19], v[90:91], v[18:19]
	v_cvt_f32_i32_e32 v20, v29
	v_mul_f32_e32 v23, v30, v23
	v_mul_f32_e32 v24, v24, v25
	v_add_f32_e32 v25, 1.0, v33
	v_mul_f32_e32 v30, 0xbfb8aa3b, v18
	v_rcp_f32_e32 v25, v25
	v_exp_f32_e32 v30, v30
	v_pk_mul_f32 v[36:37], v[132:133], v[36:37] op_sel_hi:[0,1]
	v_pk_mul_f32 v[34:35], v[132:133], v[40:41] op_sel_hi:[0,1]
	v_pk_mul_f32 v[28:29], v[124:125], v[36:37]
	v_pk_mul_f32 v[20:21], v[132:133], v[20:21] op_sel_hi:[0,1]
	v_mul_f32_e32 v26, v26, v27
	v_pk_mul_f32 v[34:35], v[130:131], v[34:35]
	v_pk_mul_f32 v[20:21], v[92:93], v[20:21]
	v_mul_f32_e32 v25, v26, v25
	v_mul_f32_e32 v18, v18, v19
	v_add_f32_e32 v19, 1.0, v30
	v_mul_f32_e32 v26, 0xbfb8aa3b, v28
	v_mul_f32_e32 v32, 0xbfb8aa3b, v34
	v_rcp_f32_e32 v19, v19
	v_exp_f32_e32 v26, v26
	v_mul_f32_e32 v27, 0xbfb8aa3b, v20
	v_exp_f32_e32 v32, v32
	v_exp_f32_e32 v27, v27
	v_mul_f32_e32 v30, v18, v19
	v_add_f32_e32 v18, 1.0, v26
	v_add_f32_e32 v32, 1.0, v32
	v_rcp_f32_e32 v18, v18
	v_add_f32_e32 v19, 1.0, v27
	v_rcp_f32_e32 v32, v32
	v_rcp_f32_e32 v31, v31
	v_rcp_f32_e32 v19, v19
	v_mul_f32_e32 v26, v28, v29
	v_mul_f32_e32 v34, v34, v35
	v_mul_f32_e32 v26, v26, v18
	v_mul_f32_e32 v18, v20, v21
	v_mul_f32_e32 v32, v34, v32
	v_mul_f32_e32 v24, v24, v31
	v_mul_f32_e32 v21, v18, v19
	v_cvt_pk_bf16_f32 v18, v32, v22
	v_cvt_pk_bf16_f32 v19, v23, v24
	v_cvt_pk_bf16_f32 v20, v25, v30
	v_cvt_f32_i32_e32 v25, v6
	v_cvt_f32_i32_e32 v6, v15
	v_cvt_f32_i32_e32 v15, v8
	v_cvt_f32_i32_e32 v8, v17
	v_cvt_f32_i32_e32 v24, v14
	v_pk_mul_f32 v[6:7], v[122:123], v[6:7] op_sel_hi:[0,1]
	v_pk_mul_f32 v[6:7], v[98:99], v[6:7]
	v_cvt_f32_i32_e32 v14, v16
	v_mul_f32_e32 v17, 0xbfb8aa3b, v6
	v_exp_f32_e32 v17, v17
	v_pk_mul_f32 v[8:9], v[122:123], v[8:9] op_sel_hi:[0,1]
	v_pk_mul_f32 v[14:15], v[122:123], v[14:15] op_sel_hi:[0,1]
	v_cvt_pk_bf16_f32 v21, v26, v21
	v_add_f32_e32 v17, 1.0, v17
	v_rcp_f32_e32 v17, v17
	v_add_u32_e32 v22, 0x5000, v123
	v_cvt_f32_i32_e32 v27, v2
	v_cvt_f32_i32_e32 v26, v10
	v_pk_mul_f32 v[14:15], v[126:127], v[14:15]
	v_pk_mul_f32 v[8:9], v[100:101], v[8:9]
	v_mul_f32_e32 v6, v6, v7
	v_and_b32_e32 v146, 0x7780, v22
	v_mul_f32_e32 v6, v6, v17
	v_mul_f32_e32 v7, 0xbfb8aa3b, v14
	v_mul_f32_e32 v17, 0xbfb8aa3b, v8
	v_lshl_add_u64 v[22:23], v[50:51], 0, v[146:147]
	v_exp_f32_e32 v7, v7
	v_exp_f32_e32 v17, v17
	v_lshl_add_u64 v[22:23], v[22:23], 0, v[156:157]
	global_store_dwordx4 v[22:23], v[18:21], off nt
	v_cvt_f32_i32_e32 v2, v11
	v_mul_f32_e32 v14, v14, v15
	v_pk_mul_f32 v[20:21], v[122:123], v[26:27] op_sel_hi:[0,1]
	v_pk_mul_f32 v[10:11], v[128:129], v[20:21]
	v_add_f32_e32 v7, 1.0, v7
	v_add_f32_e32 v15, 1.0, v17
	v_mul_f32_e32 v17, 0xbfb8aa3b, v10
	v_rcp_f32_e32 v7, v7
	v_exp_f32_e32 v17, v17
	v_pk_mul_f32 v[2:3], v[122:123], v[2:3] op_sel_hi:[0,1]
	v_cvt_f32_i32_e32 v21, v4
	v_cvt_f32_i32_e32 v20, v12
	v_pk_mul_f32 v[2:3], v[90:91], v[2:3]
	v_cvt_f32_i32_e32 v4, v13
	v_mul_f32_e32 v7, v14, v7
	v_mul_f32_e32 v8, v8, v9
	v_add_f32_e32 v9, 1.0, v17
	v_mul_f32_e32 v14, 0xbfb8aa3b, v2
	v_rcp_f32_e32 v9, v9
	v_exp_f32_e32 v14, v14
	v_pk_mul_f32 v[20:21], v[122:123], v[20:21] op_sel_hi:[0,1]
	v_pk_mul_f32 v[18:19], v[122:123], v[24:25] op_sel_hi:[0,1]
	v_pk_mul_f32 v[12:13], v[124:125], v[20:21]
	v_pk_mul_f32 v[4:5], v[122:123], v[4:5] op_sel_hi:[0,1]
	v_mul_f32_e32 v10, v10, v11
	v_pk_mul_f32 v[18:19], v[130:131], v[18:19]
	v_pk_mul_f32 v[4:5], v[92:93], v[4:5]
	v_mul_f32_e32 v9, v10, v9
	v_mul_f32_e32 v2, v2, v3
	v_add_f32_e32 v3, 1.0, v14
	v_mul_f32_e32 v10, 0xbfb8aa3b, v12
	v_mul_f32_e32 v16, 0xbfb8aa3b, v18
	v_rcp_f32_e32 v3, v3
	v_exp_f32_e32 v10, v10
	v_mul_f32_e32 v11, 0xbfb8aa3b, v4
	v_exp_f32_e32 v16, v16
	v_exp_f32_e32 v11, v11
	v_mul_f32_e32 v14, v2, v3
	v_add_f32_e32 v2, 1.0, v10
	v_add_f32_e32 v16, 1.0, v16
	v_rcp_f32_e32 v2, v2
	v_add_f32_e32 v3, 1.0, v11
	v_rcp_f32_e32 v16, v16
	v_rcp_f32_e32 v3, v3
	v_rcp_f32_e32 v15, v15
	v_mul_f32_e32 v10, v12, v13
	v_mul_f32_e32 v18, v18, v19
	v_mul_f32_e32 v10, v10, v2
	v_mul_f32_e32 v2, v4, v5
	v_mul_f32_e32 v16, v18, v16
	v_mul_f32_e32 v5, v2, v3
	v_cvt_pk_bf16_f32 v2, v16, v6
	v_add_u32_e32 v6, 0x5800, v123
	v_and_b32_e32 v146, 0x7f80, v6
	v_mul_f32_e32 v8, v8, v15
	v_cvt_pk_bf16_f32 v3, v7, v8
	v_lshl_add_u64 v[6:7], v[50:51], 0, v[146:147]
	v_lshl_add_u64 v[6:7], v[6:7], 0, v[156:157]
	v_cvt_pk_bf16_f32 v4, v9, v14
	v_cvt_pk_bf16_f32 v5, v10, v5
	global_store_dwordx4 v[6:7], v[2:5], off nt
	s_cbranch_vccnz .LBB0_1165
	s_andn2_b64 vcc, exec, s[0:1]
	s_cbranch_vccnz .LBB0_1164
	s_barrier
	s_branch .LBB0_1164
